# baseline (speedup 1.0000x reference)
; #define LAS __attribute__((address_space(3)))
; __global__ void __launch_bounds__(NTHREADS, 2) fwd_kernel(Args args) {
;     ...
;     const int tid = threadIdx.x, lane = tid & 63, wave = __builtin_amdgcn_readfirstlane(tid >> 6);
;     const int nb = gridDim.x, bx = blockIdx.x, gw = bx * NWAVES + wave, NGW = nb * NWAVES, gt = bx * NTHREADS + tid, NT = nb * NTHREADS;
;     const int lo = args.ph_lo, hi = args.ph_hi;
;     ...
;     unsigned* xbw = (unsigned*)(args.ws + WS_END + 1024);
;     volatile LAS unsigned* xbst = (volatile LAS unsigned*)(lds + LDS_BYTES - 32);
;     if (tid == 0) { xbst[0] = 0u; xbst[1] = 0u; }
_Z10fwd_kernel4Args:
	s_nop 0
	s_mov_b32 s98, 0
	s_load_dwordx4 s[20:23], s[0:1], 0x100
	s_load_dwordx2 s[40:41], s[0:1], 0x110
	s_load_dword s84, s[0:1], 0x118
	s_add_u32 s4, s0, 0x110
	s_addc_u32 s5, s1, 0
	v_and_b32_e32 v140, 0x3ff, v0
	v_writelane_b32 v232, s4, 0
	v_readfirstlane_b32 s66, v140
	v_cmp_eq_u32_e64 s[88:89], 0, v140
	v_writelane_b32 v232, s5, 1
	s_and_saveexec_b64 s[4:5], s[88:89]
	s_cbranch_execz .LBB0_2
	s_add_i32 s3, 0, 0x23fe0
	v_mov_b32_e32 v1, 0
	v_mov_b32_e32 v2, s3
	s_add_i32 s3, 0, 0x23fe4
	ds_write_b32 v2, v1
	v_mov_b32_e32 v2, s3
	ds_write_b32 v2, v1
